# grid-barrier spin loops poll without the 64-clock sleep (s_sleep 0)
# speedup vs baseline: 1.0064x; 1.0021x over previous
.LBB0_16:
	s_sleep 0
	global_load_dword v2, v0, s[6:7] offset:32 sc1
	s_waitcnt vmcnt(0)
	v_and_b32_e32 v2, 0xffff0000, v2
	v_cmp_ne_u32_e32 vcc, v2, v1
	s_or_b64 s[8:9], vcc, s[8:9]
	s_andn2_b64 exec, exec, s[8:9]
	s_cbranch_execnz .LBB0_16

.LBB0_83:
	global_load_dword v15, v16, s[58:59] offset:1024 sc1
	global_load_dword v0, v16, s[58:59] offset:1280 sc1
	global_load_dword v1, v16, s[58:59] offset:1536 sc1
	global_load_dword v2, v16, s[58:59] offset:1792 sc1
	global_load_dword v3, v16, s[58:59] offset:2048 sc1
	global_load_dword v4, v16, s[58:59] offset:2304 sc1
	global_load_dword v5, v16, s[58:59] offset:2560 sc1
	global_load_dword v6, v16, s[58:59] offset:2816 sc1
	global_load_dword v7, v16, s[58:59] offset:3072 sc1
	global_load_dword v8, v16, s[58:59] offset:3328 sc1
	global_load_dword v9, v16, s[58:59] offset:3584 sc1
	global_load_dword v10, v16, s[58:59] offset:3840 sc1
	global_load_dword v11, v16, s[6:7] sc1
	global_load_dword v12, v16, s[8:9] sc1
	global_load_dword v13, v16, s[10:11] sc1
	global_load_dword v14, v16, s[12:13] sc1
	s_mov_b64 s[14:15], -1
	s_mov_b64 s[18:19], -1
	s_waitcnt vmcnt(14)
	v_add_u32_e32 v17, v0, v15
	s_waitcnt vmcnt(13)
	v_add_u32_e32 v17, v17, v1
	s_waitcnt vmcnt(12)
	v_add_u32_e32 v17, v17, v2
	s_waitcnt vmcnt(11)
	v_add_u32_e32 v17, v17, v3
	s_waitcnt vmcnt(10)
	v_add_u32_e32 v17, v17, v4
	s_waitcnt vmcnt(9)
	v_add_u32_e32 v17, v17, v5
	s_waitcnt vmcnt(8)
	v_add_u32_e32 v17, v17, v6
	s_waitcnt vmcnt(7)
	v_add_u32_e32 v17, v17, v7
	s_waitcnt vmcnt(6)
	v_add_u32_e32 v17, v17, v8
	s_waitcnt vmcnt(5)
	v_add_u32_e32 v17, v17, v9
	s_waitcnt vmcnt(4)
	v_add_u32_e32 v17, v17, v10
	s_waitcnt vmcnt(3)
	v_add_u32_e32 v17, v17, v11
	s_waitcnt vmcnt(2)
	v_add_u32_e32 v17, v17, v12
	s_waitcnt vmcnt(1)
	v_add_u32_e32 v17, v17, v13
	s_waitcnt vmcnt(0)
	v_add_u32_e32 v17, v17, v14
	v_cmp_eq_u32_e32 vcc, s3, v17
	s_cbranch_vccnz .LBB0_82
	s_and_b32 s14, s16, 0xff
	s_cmp_eq_u32 s14, 0
	s_mov_b64 s[14:15], -1
	s_mov_b64 s[20:21], -1
	s_sleep 0
	s_cbranch_scc1 .LBB0_87
	s_and_b64 vcc, exec, s[20:21]
	s_cbranch_vccz .LBB0_82

.LBB0_97:
	s_and_b32 s16, s3, 0xff
	s_mov_b64 s[20:21], -1
	s_cmp_lg_u32 s16, 0
	s_mov_b64 s[26:27], -1
	s_sleep 0
	s_cbranch_scc0 .LBB0_100
	s_and_b64 vcc, exec, s[26:27]
	s_cbranch_vccz .LBB0_96

.LBB0_111:
	s_and_b32 s16, s3, 0xff
	s_cmp_lg_u32 s16, 0
	s_mov_b64 s[26:27], -1
	s_sleep 0
	s_cbranch_scc0 .LBB0_114
	s_mov_b64 s[34:35], -1
	s_and_b64 vcc, exec, s[26:27]
	s_cbranch_vccz .LBB0_110

.LBB0_141:
	global_load_dword v15, v16, s[58:59] offset:1024 sc1
	global_load_dword v0, v16, s[58:59] offset:1280 sc1
	global_load_dword v1, v16, s[58:59] offset:1536 sc1
	global_load_dword v2, v16, s[58:59] offset:1792 sc1
	global_load_dword v3, v16, s[58:59] offset:2048 sc1
	global_load_dword v4, v16, s[58:59] offset:2304 sc1
	global_load_dword v5, v16, s[58:59] offset:2560 sc1
	global_load_dword v6, v16, s[58:59] offset:2816 sc1
	global_load_dword v7, v16, s[58:59] offset:3072 sc1
	global_load_dword v8, v16, s[58:59] offset:3328 sc1
	global_load_dword v9, v16, s[58:59] offset:3584 sc1
	global_load_dword v10, v16, s[58:59] offset:3840 sc1
	global_load_dword v11, v16, s[4:5] sc1
	global_load_dword v12, v16, s[8:9] sc1
	global_load_dword v13, v16, s[10:11] sc1
	global_load_dword v14, v16, s[12:13] sc1
	s_mov_b64 s[14:15], -1
	s_mov_b64 s[18:19], -1
	s_waitcnt vmcnt(14)
	v_add_u32_e32 v17, v0, v15
	s_waitcnt vmcnt(13)
	v_add_u32_e32 v17, v17, v1
	s_waitcnt vmcnt(12)
	v_add_u32_e32 v17, v17, v2
	s_waitcnt vmcnt(11)
	v_add_u32_e32 v17, v17, v3
	s_waitcnt vmcnt(10)
	v_add_u32_e32 v17, v17, v4
	s_waitcnt vmcnt(9)
	v_add_u32_e32 v17, v17, v5
	s_waitcnt vmcnt(8)
	v_add_u32_e32 v17, v17, v6
	s_waitcnt vmcnt(7)
	v_add_u32_e32 v17, v17, v7
	s_waitcnt vmcnt(6)
	v_add_u32_e32 v17, v17, v8
	s_waitcnt vmcnt(5)
	v_add_u32_e32 v17, v17, v9
	s_waitcnt vmcnt(4)
	v_add_u32_e32 v17, v17, v10
	s_waitcnt vmcnt(3)
	v_add_u32_e32 v17, v17, v11
	s_waitcnt vmcnt(2)
	v_add_u32_e32 v17, v17, v12
	s_waitcnt vmcnt(1)
	v_add_u32_e32 v17, v17, v13
	s_waitcnt vmcnt(0)
	v_add_u32_e32 v17, v17, v14
	v_cmp_eq_u32_e32 vcc, s3, v17
	s_cbranch_vccnz .LBB0_140
	s_and_b32 s14, s16, 0xff
	s_cmp_eq_u32 s14, 0
	s_mov_b64 s[14:15], -1
	s_mov_b64 s[20:21], -1
	s_sleep 0
	s_cbranch_scc1 .LBB0_145
	s_and_b64 vcc, exec, s[20:21]
	s_cbranch_vccz .LBB0_140

.LBB0_392:
	global_load_dword v15, v16, s[58:59] offset:1024 sc1
	global_load_dword v0, v16, s[58:59] offset:1280 sc1
	global_load_dword v1, v16, s[58:59] offset:1536 sc1
	global_load_dword v2, v16, s[58:59] offset:1792 sc1
	global_load_dword v3, v16, s[58:59] offset:2048 sc1
	global_load_dword v4, v16, s[58:59] offset:2304 sc1
	global_load_dword v5, v16, s[58:59] offset:2560 sc1
	global_load_dword v6, v16, s[58:59] offset:2816 sc1
	global_load_dword v7, v16, s[58:59] offset:3072 sc1
	global_load_dword v8, v16, s[58:59] offset:3328 sc1
	global_load_dword v9, v16, s[58:59] offset:3584 sc1
	global_load_dword v10, v16, s[58:59] offset:3840 sc1
	global_load_dword v11, v16, s[6:7] sc1
	global_load_dword v12, v16, s[8:9] sc1
	global_load_dword v13, v16, s[10:11] sc1
	global_load_dword v14, v16, s[12:13] sc1
	s_mov_b64 s[14:15], -1
	s_mov_b64 s[16:17], -1
	s_waitcnt vmcnt(14)
	v_add_u32_e32 v17, v0, v15
	s_waitcnt vmcnt(13)
	v_add_u32_e32 v17, v17, v1
	s_waitcnt vmcnt(12)
	v_add_u32_e32 v17, v17, v2
	s_waitcnt vmcnt(11)
	v_add_u32_e32 v17, v17, v3
	s_waitcnt vmcnt(10)
	v_add_u32_e32 v17, v17, v4
	s_waitcnt vmcnt(9)
	v_add_u32_e32 v17, v17, v5
	s_waitcnt vmcnt(8)
	v_add_u32_e32 v17, v17, v6
	s_waitcnt vmcnt(7)
	v_add_u32_e32 v17, v17, v7
	s_waitcnt vmcnt(6)
	v_add_u32_e32 v17, v17, v8
	s_waitcnt vmcnt(5)
	v_add_u32_e32 v17, v17, v9
	s_waitcnt vmcnt(4)
	v_add_u32_e32 v17, v17, v10
	s_waitcnt vmcnt(3)
	v_add_u32_e32 v17, v17, v11
	s_waitcnt vmcnt(2)
	v_add_u32_e32 v17, v17, v12
	s_waitcnt vmcnt(1)
	v_add_u32_e32 v17, v17, v13
	s_waitcnt vmcnt(0)
	v_add_u32_e32 v17, v17, v14
	v_cmp_eq_u32_e32 vcc, s3, v17
	s_cbranch_vccnz .LBB0_391
	s_and_b32 s14, s20, 0xff
	s_cmp_eq_u32 s14, 0
	s_mov_b64 s[14:15], -1
	s_mov_b64 s[18:19], -1
	s_sleep 0
	s_cbranch_scc1 .LBB0_396
	s_and_b64 vcc, exec, s[18:19]
	s_cbranch_vccz .LBB0_391

.LBB0_406:
	s_and_b32 s20, s3, 0xff
	s_mov_b64 s[18:19], -1
	s_cmp_lg_u32 s20, 0
	s_mov_b64 s[24:25], -1
	s_sleep 0
	s_cbranch_scc0 .LBB0_409
	s_and_b64 vcc, exec, s[24:25]
	s_cbranch_vccz .LBB0_405

.LBB0_420:
	s_and_b32 s20, s3, 0xff
	s_cmp_lg_u32 s20, 0
	s_mov_b64 s[24:25], -1
	s_sleep 0
	s_cbranch_scc0 .LBB0_423
	s_mov_b64 s[26:27], -1
	s_and_b64 vcc, exec, s[24:25]
	s_cbranch_vccz .LBB0_419

.LBB0_663:
	global_load_dword v15, v16, s[58:59] offset:1024 sc1
	global_load_dword v0, v16, s[58:59] offset:1280 sc1
	global_load_dword v1, v16, s[58:59] offset:1536 sc1
	global_load_dword v2, v16, s[58:59] offset:1792 sc1
	global_load_dword v3, v16, s[58:59] offset:2048 sc1
	global_load_dword v4, v16, s[58:59] offset:2304 sc1
	global_load_dword v5, v16, s[58:59] offset:2560 sc1
	global_load_dword v6, v16, s[58:59] offset:2816 sc1
	global_load_dword v7, v16, s[58:59] offset:3072 sc1
	global_load_dword v8, v16, s[58:59] offset:3328 sc1
	global_load_dword v9, v16, s[58:59] offset:3584 sc1
	global_load_dword v10, v16, s[58:59] offset:3840 sc1
	global_load_dword v11, v16, s[4:5] sc1
	global_load_dword v12, v16, s[8:9] sc1
	global_load_dword v13, v16, s[10:11] sc1
	global_load_dword v14, v16, s[12:13] sc1
	s_mov_b64 s[14:15], -1
	s_mov_b64 s[16:17], -1
	s_waitcnt vmcnt(14)
	v_add_u32_e32 v17, v0, v15
	s_waitcnt vmcnt(13)
	v_add_u32_e32 v17, v17, v1
	s_waitcnt vmcnt(12)
	v_add_u32_e32 v17, v17, v2
	s_waitcnt vmcnt(11)
	v_add_u32_e32 v17, v17, v3
	s_waitcnt vmcnt(10)
	v_add_u32_e32 v17, v17, v4
	s_waitcnt vmcnt(9)
	v_add_u32_e32 v17, v17, v5
	s_waitcnt vmcnt(8)
	v_add_u32_e32 v17, v17, v6
	s_waitcnt vmcnt(7)
	v_add_u32_e32 v17, v17, v7
	s_waitcnt vmcnt(6)
	v_add_u32_e32 v17, v17, v8
	s_waitcnt vmcnt(5)
	v_add_u32_e32 v17, v17, v9
	s_waitcnt vmcnt(4)
	v_add_u32_e32 v17, v17, v10
	s_waitcnt vmcnt(3)
	v_add_u32_e32 v17, v17, v11
	s_waitcnt vmcnt(2)
	v_add_u32_e32 v17, v17, v12
	s_waitcnt vmcnt(1)
	v_add_u32_e32 v17, v17, v13
	s_waitcnt vmcnt(0)
	v_add_u32_e32 v17, v17, v14
	v_cmp_eq_u32_e32 vcc, s3, v17
	s_cbranch_vccnz .LBB0_662
	s_and_b32 s14, s20, 0xff
	s_cmp_eq_u32 s14, 0
	s_mov_b64 s[14:15], -1
	s_mov_b64 s[18:19], -1
	s_sleep 0
	s_cbranch_scc1 .LBB0_667
	s_and_b64 vcc, exec, s[18:19]
	s_cbranch_vccz .LBB0_662

.LBB0_757:
	s_and_b32 s20, s3, 0xff
	s_mov_b64 s[18:19], -1
	s_cmp_lg_u32 s20, 0
	s_mov_b64 s[22:23], -1
	s_sleep 0
	s_cbranch_scc0 .LBB0_760
	s_and_b64 vcc, exec, s[22:23]
	s_cbranch_vccz .LBB0_756

.LBB0_771:
	s_and_b32 s20, s3, 0xff
	s_cmp_lg_u32 s20, 0
	s_mov_b64 s[22:23], -1
	s_sleep 0
	s_cbranch_scc0 .LBB0_774
	s_mov_b64 s[24:25], -1
	s_and_b64 vcc, exec, s[22:23]
	s_cbranch_vccz .LBB0_770

.LBB0_935:
	global_load_dword v15, v16, s[58:59] offset:1024 sc1
	global_load_dword v0, v16, s[58:59] offset:1280 sc1
	global_load_dword v1, v16, s[58:59] offset:1536 sc1
	global_load_dword v2, v16, s[58:59] offset:1792 sc1
	global_load_dword v3, v16, s[58:59] offset:2048 sc1
	global_load_dword v4, v16, s[58:59] offset:2304 sc1
	global_load_dword v5, v16, s[58:59] offset:2560 sc1
	global_load_dword v6, v16, s[58:59] offset:2816 sc1
	global_load_dword v7, v16, s[58:59] offset:3072 sc1
	global_load_dword v8, v16, s[58:59] offset:3328 sc1
	global_load_dword v9, v16, s[58:59] offset:3584 sc1
	global_load_dword v10, v16, s[58:59] offset:3840 sc1
	global_load_dword v11, v16, s[0:1] sc1
	global_load_dword v12, v16, s[4:5] sc1
	global_load_dword v13, v16, s[6:7] sc1
	global_load_dword v14, v16, s[8:9] sc1
	s_mov_b64 s[10:11], -1
	s_mov_b64 s[12:13], -1
	s_waitcnt vmcnt(14)
	v_add_u32_e32 v17, v0, v15
	s_waitcnt vmcnt(13)
	v_add_u32_e32 v17, v17, v1
	s_waitcnt vmcnt(12)
	v_add_u32_e32 v17, v17, v2
	s_waitcnt vmcnt(11)
	v_add_u32_e32 v17, v17, v3
	s_waitcnt vmcnt(10)
	v_add_u32_e32 v17, v17, v4
	s_waitcnt vmcnt(9)
	v_add_u32_e32 v17, v17, v5
	s_waitcnt vmcnt(8)
	v_add_u32_e32 v17, v17, v6
	s_waitcnt vmcnt(7)
	v_add_u32_e32 v17, v17, v7
	s_waitcnt vmcnt(6)
	v_add_u32_e32 v17, v17, v8
	s_waitcnt vmcnt(5)
	v_add_u32_e32 v17, v17, v9
	s_waitcnt vmcnt(4)
	v_add_u32_e32 v17, v17, v10
	s_waitcnt vmcnt(3)
	v_add_u32_e32 v17, v17, v11
	s_waitcnt vmcnt(2)
	v_add_u32_e32 v17, v17, v12
	s_waitcnt vmcnt(1)
	v_add_u32_e32 v17, v17, v13
	s_waitcnt vmcnt(0)
	v_add_u32_e32 v17, v17, v14
	v_cmp_eq_u32_e32 vcc, s16, v17
	s_cbranch_vccnz .LBB0_934
	s_and_b32 s10, s17, 0xff
	s_cmp_eq_u32 s10, 0
	s_mov_b64 s[10:11], -1
	s_mov_b64 s[14:15], -1
	s_sleep 0
	s_cbranch_scc1 .LBB0_939
	s_and_b64 vcc, exec, s[14:15]
	s_cbranch_vccz .LBB0_934

.LBB0_949:
	s_and_b32 s16, s20, 0xff
	s_mov_b64 s[14:15], -1
	s_cmp_lg_u32 s16, 0
	s_mov_b64 s[18:19], -1
	s_sleep 0
	s_cbranch_scc0 .LBB0_952
	s_and_b64 vcc, exec, s[18:19]
	s_cbranch_vccz .LBB0_948

.LBB0_963:
	s_and_b32 s16, s22, 0xff
	s_cmp_lg_u32 s16, 0
	s_mov_b64 s[18:19], -1
	s_sleep 0
	s_cbranch_scc0 .LBB0_966
	s_mov_b64 s[20:21], -1
	s_and_b64 vcc, exec, s[18:19]
	s_cbranch_vccz .LBB0_962
